# GLA scan: static s_setprio 1 for waves 4-7 (second-longest scan kernel)
# baseline (speedup 1.0000x reference)
; DI int otid() { int t = threadIdx.x; asm volatile("" : "+v"(t)); return t; }
; DI void gla_scan_item(const P& p, int seq, unsigned char* smem) {
;     const int dir = seq >> 4, b = (seq >> 2) & 3, h = seq & 3;
;     constexpr int BUFB = 20736;
;     const bf16_t* S = (const bf16_t*)(p.ws + WS_SBUF);
;     const bf16_t* QT = (const bf16_t*)(p.ws + WS_GLA_QT); const bf16_t* KO = (const bf16_t*)(p.ws + WS_GLA_KO); const bf16_t* AT = (const bf16_t*)(p.ws + WS_GLA_AT); const float* DC = (const float*)(p.ws + WS_GLA_DC);
;     bf16_t* OG = (bf16_t*)(p.ws + WS_NBUF) + (size_t)dir * NROW * 512;
;     const int tid = otid(), w = tid >> 6, lane = tid & 63, l15 = lane & 15, g = lane >> 4, q4 = l15 >> 2, p4 = l15 & 3;
;     auto loadr = [&](GlaRegs& R, int c) {
;         if (c >= 72) return;
;         { const int pos = tid >> 4, ch = tid & 15; R.rv = *(const u32x4*)(S + (size_t)prow(b, dir, 32 * c + pos) * NP + C_GLA_V + 128 * h + 8 * ch); }
;         { const int t2 = tid & 255, pos = t2 >> 3, ch = t2 & 7; const bf16_t* src = (tid < 256 ? QT : KO) + ((size_t)seq * PT + 32 * c + pos) * 64 + 8 * ch; R.rq = __builtin_nontemporal_load((const u32x4*)src); }
;         if (tid < 128) { const int i = tid >> 2, ch = tid & 3; R.ra = __builtin_nontemporal_load((const u32x4*)(AT + (((size_t)seq * 72 + c) * 32 + i) * 32 + 8 * ch)); }
;         if (tid >= 128 && tid < 192) R.rd = DC[((size_t)seq * 72 + c) * 64 + (tid - 128)];
;     };
;     ...
;     loadr(R0, 0); loadr(R1, 1); loadr(R2, 2); loadr(R3, 3); loadr(R4, 4); loadr(R5, 5);
.LBB0_528:
	s_and_b64 vcc, exec, s[36:37]
	s_cbranch_vccz .LBB0_475
.LBB0_529:
	v_readfirstlane_b32 s98, v166
	s_nop 0
	s_lshr_b32 s98, s98, 6
	s_cmp_ge_u32 s98, 4
	s_cbranch_scc0 .Lgla_prio_done
	s_setprio 1
.Lgla_prio_done:
	s_bfe_u32 s2, s56, 0x20002
	s_waitcnt vmcnt(2)
	v_mov_b32_e32 v72, v166
	s_cmp_lt_u32 s56, 16
	s_movk_i32 s3, 0xff
	v_ashrrev_i32_e32 v114, 4, v72
	s_cselect_b64 s[0:1], -1, 0
	s_lshl_b32 s21, s2, 11
	v_cmp_lt_i32_e32 vcc, s3, v114
	s_and_saveexec_b64 s[4:5], vcc
	s_xor_b64 s[36:37], exec, s[4:5]
	v_add_u32_e32 v0, 0xffffff00, v114
	v_sub_u32_e32 v1, 0x8ff, v114
	v_cndmask_b32_e64 v0, v1, v0, s[0:1]
	v_add_u32_e32 v0, s21, v0
	s_or_saveexec_b64 s[36:37], s[36:37]
	s_lshl_b32 s22, s2, 8
	s_bitset1_b32 s22, 13
	s_xor_b64 exec, exec, s[36:37]
	v_sub_u32_e32 v0, 0xff, v114
	v_cndmask_b32_e64 v0, v0, v114, s[0:1]
	v_add_u32_e32 v0, s22, v0
	s_or_b64 exec, exec, s[36:37]
	s_add_u32 s36, s46, 0x6c3c000
	s_addc_u32 s37, s47, 0
	s_lshl_b32 s2, s56, 7
	s_and_b32 s4, s2, 0x180
	s_mul_i32 s48, s56, 0x24000
	s_mul_hi_i32 s49, s56, 0x24000
	s_add_u32 s2, s46, s48
	s_addc_u32 s3, s47, s49
	s_add_u32 s50, s2, 0x1283c000
	v_mov_b64_e32 v[2:3], s[36:37]
	s_movk_i32 s2, 0x3800
	s_addc_u32 s51, s3, 0
	v_mad_i64_i32 v[0:1], s[2:3], v0, s2, v[2:3]
	v_lshlrev_b32_e32 v6, 3, v72
	v_and_b32_e32 v2, 0x78, v6
	s_movk_i32 s2, 0x100
	s_mul_hi_i32 s5, s56, 0x900
	s_mul_i32 s6, s56, 0x900
	v_lshlrev_b32_e32 v74, 1, v2
	v_bfe_u32 v82, v72, 3, 5
	v_cmp_gt_i32_e64 s[42:43], s2, v72
	v_mov_b32_e32 v2, 0x11f3c000
	v_mov_b32_e32 v3, 0x1163c000
	v_cndmask_b32_e64 v132, v2, v3, s[42:43]
	v_or_b32_e32 v4, s6, v82
	v_mov_b32_e32 v5, s5
	s_lshl_b32 s18, s4, 1
	v_lshl_add_u64 v[2:3], s[46:47], 0, v[132:133]
	v_lshlrev_b64 v[4:5], 7, v[4:5]
	v_lshl_add_u64 v[0:1], v[0:1], 0, s[18:19]
	v_mov_b32_e32 v75, v133
	v_lshl_add_u64 v[60:61], v[2:3], 0, v[4:5]
	v_and_b32_e32 v2, 56, v6
	v_lshl_add_u64 v[0:1], v[0:1], 0, v[74:75]
	v_lshlrev_b32_e32 v80, 1, v2
	v_mov_b32_e32 v81, v133
	v_lshl_add_u64 v[4:5], v[60:61], 0, v[80:81]
	global_load_dwordx4 v[0:3], v[0:1], off offset:1024
	s_nop 0
	global_load_dwordx4 v[8:11], v[4:5], off nt
	s_movk_i32 s2, 0x80
	v_ashrrev_i32_e32 v76, 2, v72
	v_and_b32_e32 v83, 24, v6
	v_cmp_gt_i32_e64 s[38:39], s2, v72
	v_ashrrev_i32_e32 v77, 31, v76
	v_lshlrev_b32_e32 v78, 1, v83
	s_and_saveexec_b64 s[40:41], s[38:39]
	s_cbranch_execz .LBB0_535
	v_lshlrev_b64 v[4:5], 6, v[76:77]
	v_lshl_add_u64 v[4:5], s[50:51], 0, v[4:5]
	v_mov_b32_e32 v79, v133
	v_lshl_add_u64 v[4:5], v[4:5], 0, v[78:79]
	global_load_dwordx4 v[4:7], v[4:5], off nt

; DI void gla_scan_item(const P& p, int seq, unsigned char* smem) {
;     ...
;     }
;     __syncthreads();
; }
.LBB0_639:
	s_setprio 0
	s_barrier
	s_cbranch_execnz .LBB0_476
	s_branch .LBB0_477
